# attention: MFMA half runs at s_setprio 1, softmax half at 0
# baseline (speedup 1.0000x reference)
; __device__ __forceinline__ int ltid() { int t = threadIdx.x; asm volatile("" : "+v"(t)); return t; }
; __device__ __forceinline__ void qkt(f32x16& p0, f32x16& p1, const unsigned char* Ks, const i32x8* qr, int r32, int hi) {
;   p0 = f32x16{}; p1 = f32x16{};
; #pragma unroll
;   for (int m = 0; m < 3; ++m) { const int cb = m * 64 + hi * 32;
;     const u32x4 a0 = *reinterpret_cast<const u32x4*>(Ks + KSWZ(r32, cb)), a1 = *reinterpret_cast<const u32x4*>(Ks + KSWZ(r32, cb) + 16);
;     const u32x4 c0 = *reinterpret_cast<const u32x4*>(Ks + KSWZ(32 + r32, cb)), c1 = *reinterpret_cast<const u32x4*>(Ks + KSWZ(32 + r32, cb) + 16);
;     const i32x8 b0 = {(int)a0.x, (int)a0.y, (int)a0.z, (int)a0.w, (int)a1.x, (int)a1.y, (int)a1.z, (int)a1.w};
;     const i32x8 b1 = {(int)c0.x, (int)c0.y, (int)c0.z, (int)c0.w, (int)c1.x, (int)c1.y, (int)c1.z, (int)c1.w};
;     p0 = __builtin_amdgcn_mfma_scale_f32_32x32x64_f8f6f4(b0, qr[m], p0, 0, 0, 0, 0x7F7F7F7F, 0, 0x7F7F7F7F);
;     p1 = __builtin_amdgcn_mfma_scale_f32_32x32x64_f8f6f4(b1, qr[m], p1, 0, 0, 0, 0x7F7F7F7F, 0, 0x7F7F7F7F); }
; }
; __device__ __forceinline__ void pv_d0(f32x16* o, const unsigned char* Vs, const i32x8& pa, int r32, int hi) {
; #pragma unroll
;   for (int d0 = 0; d0 < 4; ++d0) { const unsigned char* vp = Vs + (32 * d0 + r32) * 80 + hi * 32;
;     const u32x4 a0 = *reinterpret_cast<const u32x4*>(vp), a1 = *reinterpret_cast<const u32x4*>(vp + 16);
;     const i32x8 vb = {(int)a0.x, (int)a0.y, (int)a0.z, (int)a0.w, (int)a1.x, (int)a1.y, (int)a1.z, (int)a1.w};
;     o[d0] = __builtin_amdgcn_mfma_scale_f32_32x32x64_f8f6f4(pa, vb, o[d0], 0, 0, 0, 0x7A7A7A7A, 0, 0x7F7F7F7F); }
; }
; __device__ __forceinline__ void attn_body(const unsigned char* __restrict__ Qb, const unsigned char* __restrict__ Kh, const unsigned char* __restrict__ Vt,
;                                           bf16_t* __restrict__ Ob, int seq, char* lds) {
;   const int tid = ltid(), wid = tid >> 6, lane = tid & 63, r32 = lane & 31, hi = lane >> 5;
;   unsigned char* V_lds = (unsigned char*)lds; unsigned char* K_lds = (unsigned char*)(lds + 3 * SHM_V);
;   float* ws = (float*)(lds + 3 * SHM_V + 3 * SHM_K) + wid * 64; float* li_l = ws; float* al_l = ws + 32;
;   float m_reg = -1e30f, l_reg = 0; f32x16 o[4] = {}; i32x8 qr[3];
;   const unsigned char* Qw = Qb + (long)(wid * QBLK + r32) * 192 + hi * 32;
; #pragma unroll
.Latt_loop:
	s_cmp_eq_u32 s6, 0
	s_cbranch_scc1 .Latt_m_first
	s_setprio 1
	s_add_u32 s4, s6, 2
	ds_read_b128 v[176:179], v221 offset:30720
	ds_read_b128 v[180:183], v221 offset:30736
	ds_read_b128 v[184:187], v221 offset:33280
	ds_read_b128 v[188:191], v221 offset:33296
	s_waitcnt lgkmcnt(4)
	v_mfma_scale_f32_32x32x64_f8f6f4 v[64:79], v[128:135], v[96:103], v[160:175], v235, v201 op_sel_hi:[0,0,0]
	ds_read_b128 v[128:131], v220 offset:128
	ds_read_b128 v[132:135], v220 offset:144
	v_mfma_scale_f32_32x32x64_f8f6f4 v[80:95], v[136:143], v[96:103], v[160:175], v235, v201 op_sel_hi:[0,0,0]
	ds_read_b128 v[136:139], v220 offset:6784
	ds_read_b128 v[140:143], v220 offset:6800
	s_cmp_lt_u32 s4, 128
	s_cbranch_scc0 .Latt_ms0_nowr
	s_waitcnt vmcnt(0)
	ds_write2_b32 v225, v202, v204 offset1:1
	ds_write2_b32 v225, v203, v205 offset0:8 offset1:9
	ds_write_b128 v218, v[206:209] offset:26624
	s_cmp_lt_u32 s12, 4
	s_cbranch_scc0 .Latt_ms0_w1
	ds_write_b128 v219, v[210:213] offset:26624

; __device__ __forceinline__ void partialSM(f32x16& p0, f32x16& p1, float& m_reg, float& mn, float& alpha) {
;   constexpr float C = SCALE * 1.4426950408889634f;
;   float pmax = p0[0]; for (int r = 1; r < 16; ++r) pmax = fmaxf(pmax, p0[r]); for (int r = 0; r < 16; ++r) pmax = fmaxf(pmax, p1[r]);
;   { auto rr = __builtin_amdgcn_permlane32_swap(__float_as_uint(pmax), __float_as_uint(pmax), false, false);
;     pmax = fmaxf(__uint_as_float(rr[0]), __uint_as_float(rr[1])); }
;   if (__builtin_expect(__all(pmax - m_reg <= THR / SCALE), 1)) { mn = m_reg; alpha = 1.f; }
.Latt_m_nobar_0:
	s_setprio 0
	v_max3_f32 v228, v64, v65, v66
	v_max3_f32 v229, v80, v81, v82
	v_max3_f32 v228, v228, v67, v68
	v_max3_f32 v229, v229, v83, v84
	v_max3_f32 v228, v228, v69, v70
	v_max3_f32 v229, v229, v85, v86
	v_max3_f32 v228, v228, v71, v72
	v_max3_f32 v229, v229, v87, v88
	v_max3_f32 v228, v228, v73, v74
	v_max3_f32 v229, v229, v89, v90
	v_max3_f32 v228, v228, v75, v76
	v_max3_f32 v229, v229, v91, v92
	v_max3_f32 v228, v228, v77, v78
	v_max3_f32 v229, v229, v93, v94
	v_max3_f32 v228, v228, v79, v95
	v_max_f32_e32 v228, v228, v229
	s_mov_b32 s5, 0
	v_cmp_ge_f32_e32 vcc, s13, v228
	v_mov_b32_e32 v226, 1.0
	s_cmp_eq_u32 s6, 0
	s_cbranch_scc1 .Latt_rare
	s_cmp_eq_u64 vcc, exec
	s_cbranch_scc0 .Latt_rare

; __device__ __forceinline__ void qkt(f32x16& p0, f32x16& p1, const unsigned char* Ks, const i32x8* qr, int r32, int hi) {
;   p0 = f32x16{}; p1 = f32x16{};
; #pragma unroll
;   for (int m = 0; m < 3; ++m) { const int cb = m * 64 + hi * 32;
;     const u32x4 a0 = *reinterpret_cast<const u32x4*>(Ks + KSWZ(r32, cb)), a1 = *reinterpret_cast<const u32x4*>(Ks + KSWZ(r32, cb) + 16);
;     const u32x4 c0 = *reinterpret_cast<const u32x4*>(Ks + KSWZ(32 + r32, cb)), c1 = *reinterpret_cast<const u32x4*>(Ks + KSWZ(32 + r32, cb) + 16);
;     const i32x8 b0 = {(int)a0.x, (int)a0.y, (int)a0.z, (int)a0.w, (int)a1.x, (int)a1.y, (int)a1.z, (int)a1.w};
;     const i32x8 b1 = {(int)c0.x, (int)c0.y, (int)c0.z, (int)c0.w, (int)c1.x, (int)c1.y, (int)c1.z, (int)c1.w};
;     p0 = __builtin_amdgcn_mfma_scale_f32_32x32x64_f8f6f4(b0, qr[m], p0, 0, 0, 0, 0x7F7F7F7F, 0, 0x7F7F7F7F);
;     p1 = __builtin_amdgcn_mfma_scale_f32_32x32x64_f8f6f4(b1, qr[m], p1, 0, 0, 0, 0x7F7F7F7F, 0, 0x7F7F7F7F); }
.Latt_v_nobar_0:
	s_add_u32 s6, s6, 1
	s_setprio 1
	s_add_u32 s4, s6, 2
	ds_read_b128 v[176:179], v221 offset:0
	ds_read_b128 v[180:183], v221 offset:16
	ds_read_b128 v[184:187], v221 offset:2560
	ds_read_b128 v[188:191], v221 offset:2576
	s_waitcnt lgkmcnt(4)
	v_mfma_scale_f32_32x32x64_f8f6f4 v[64:79], v[128:135], v[96:103], v[160:175], v235, v201 op_sel_hi:[0,0,0]
	ds_read_b128 v[128:131], v220 offset:13440
	ds_read_b128 v[132:135], v220 offset:13456
	v_mfma_scale_f32_32x32x64_f8f6f4 v[80:95], v[136:143], v[96:103], v[160:175], v235, v201 op_sel_hi:[0,0,0]
	ds_read_b128 v[136:139], v220 offset:20096
	ds_read_b128 v[140:143], v220 offset:20112
	s_cmp_lt_u32 s4, 128
	s_cbranch_scc0 .Latt_ms1_nowr
	v_add_u32_e32 v228, 30720, v217
	s_waitcnt vmcnt(0)
	ds_write2_b32 v228, v202, v204 offset1:1
	ds_write2_b32 v228, v203, v205 offset0:8 offset1:9
	ds_write_b128 v218, v[206:209] offset:39936
	s_cmp_lt_u32 s12, 4
	s_cbranch_scc0 .Latt_ms1_w1
	ds_write_b128 v219, v[210:213] offset:39936

; __device__ __forceinline__ void partialSM(f32x16& p0, f32x16& p1, float& m_reg, float& mn, float& alpha) {
;   constexpr float C = SCALE * 1.4426950408889634f;
;   float pmax = p0[0]; for (int r = 1; r < 16; ++r) pmax = fmaxf(pmax, p0[r]); for (int r = 0; r < 16; ++r) pmax = fmaxf(pmax, p1[r]);
;   { auto rr = __builtin_amdgcn_permlane32_swap(__float_as_uint(pmax), __float_as_uint(pmax), false, false);
;     pmax = fmaxf(__uint_as_float(rr[0]), __uint_as_float(rr[1])); }
;   if (__builtin_expect(__all(pmax - m_reg <= THR / SCALE), 1)) { mn = m_reg; alpha = 1.f; }
.Latt_m_nobar_1:
	s_setprio 0
	v_max3_f32 v228, v64, v65, v66
	v_max3_f32 v229, v80, v81, v82
	v_max3_f32 v228, v228, v67, v68
	v_max3_f32 v229, v229, v83, v84
	v_max3_f32 v228, v228, v69, v70
	v_max3_f32 v229, v229, v85, v86
	v_max3_f32 v228, v228, v71, v72
	v_max3_f32 v229, v229, v87, v88
	v_max3_f32 v228, v228, v73, v74
	v_max3_f32 v229, v229, v89, v90
	v_max3_f32 v228, v228, v75, v76
	v_max3_f32 v229, v229, v91, v92
	v_max3_f32 v228, v228, v77, v78
	v_max3_f32 v229, v229, v93, v94
	v_max3_f32 v228, v228, v79, v95
	v_max_f32_e32 v228, v228, v229
	s_mov_b32 s5, 1
	v_cmp_ge_f32_e32 vcc, s13, v228
	v_mov_b32_e32 v226, 1.0
	s_cmp_eq_u64 vcc, exec
	s_cbranch_scc0 .Latt_rare

; __device__ __forceinline__ void qkt(f32x16& p0, f32x16& p1, const unsigned char* Ks, const i32x8* qr, int r32, int hi) {
;   p0 = f32x16{}; p1 = f32x16{};
; #pragma unroll
;   for (int m = 0; m < 3; ++m) { const int cb = m * 64 + hi * 32;
;     const u32x4 a0 = *reinterpret_cast<const u32x4*>(Ks + KSWZ(r32, cb)), a1 = *reinterpret_cast<const u32x4*>(Ks + KSWZ(r32, cb) + 16);
;     const u32x4 c0 = *reinterpret_cast<const u32x4*>(Ks + KSWZ(32 + r32, cb)), c1 = *reinterpret_cast<const u32x4*>(Ks + KSWZ(32 + r32, cb) + 16);
;     const i32x8 b0 = {(int)a0.x, (int)a0.y, (int)a0.z, (int)a0.w, (int)a1.x, (int)a1.y, (int)a1.z, (int)a1.w};
;     const i32x8 b1 = {(int)c0.x, (int)c0.y, (int)c0.z, (int)c0.w, (int)c1.x, (int)c1.y, (int)c1.z, (int)c1.w};
;     p0 = __builtin_amdgcn_mfma_scale_f32_32x32x64_f8f6f4(b0, qr[m], p0, 0, 0, 0, 0x7F7F7F7F, 0, 0x7F7F7F7F);
;     p1 = __builtin_amdgcn_mfma_scale_f32_32x32x64_f8f6f4(b1, qr[m], p1, 0, 0, 0, 0x7F7F7F7F, 0, 0x7F7F7F7F); }
.Latt_v_nobar_1:
	s_add_u32 s6, s6, 1
	s_setprio 1
	s_add_u32 s4, s6, 2
	ds_read_b128 v[176:179], v221 offset:10240
	ds_read_b128 v[180:183], v221 offset:10256
	ds_read_b128 v[184:187], v221 offset:12800
	ds_read_b128 v[188:191], v221 offset:12816
	s_waitcnt lgkmcnt(4)
	v_mfma_scale_f32_32x32x64_f8f6f4 v[64:79], v[128:135], v[96:103], v[160:175], v235, v201 op_sel_hi:[0,0,0]
	ds_read_b128 v[128:131], v220 offset:26752
	ds_read_b128 v[132:135], v220 offset:26768
	v_mfma_scale_f32_32x32x64_f8f6f4 v[80:95], v[136:143], v[96:103], v[160:175], v235, v201 op_sel_hi:[0,0,0]
	ds_read_b128 v[136:139], v220 offset:33408
	ds_read_b128 v[140:143], v220 offset:33424
	s_cmp_lt_u32 s4, 128
	s_cbranch_scc0 .Latt_ms2_nowr
	s_waitcnt vmcnt(0)
	ds_write2_b32 v217, v202, v204 offset1:1
	ds_write2_b32 v217, v203, v205 offset0:8 offset1:9
	ds_write_b128 v218, v[206:209] offset:0
	s_cmp_lt_u32 s12, 4
	s_cbranch_scc0 .Latt_ms2_w1
	ds_write_b128 v219, v[210:213] offset:0

; __device__ __forceinline__ void partialSM(f32x16& p0, f32x16& p1, float& m_reg, float& mn, float& alpha) {
;   constexpr float C = SCALE * 1.4426950408889634f;
;   float pmax = p0[0]; for (int r = 1; r < 16; ++r) pmax = fmaxf(pmax, p0[r]); for (int r = 0; r < 16; ++r) pmax = fmaxf(pmax, p1[r]);
;   { auto rr = __builtin_amdgcn_permlane32_swap(__float_as_uint(pmax), __float_as_uint(pmax), false, false);
;     pmax = fmaxf(__uint_as_float(rr[0]), __uint_as_float(rr[1])); }
;   if (__builtin_expect(__all(pmax - m_reg <= THR / SCALE), 1)) { mn = m_reg; alpha = 1.f; }
.Latt_m_nobar_2:
	s_setprio 0
	v_max3_f32 v228, v64, v65, v66
	v_max3_f32 v229, v80, v81, v82
	v_max3_f32 v228, v228, v67, v68
	v_max3_f32 v229, v229, v83, v84
	v_max3_f32 v228, v228, v69, v70
	v_max3_f32 v229, v229, v85, v86
	v_max3_f32 v228, v228, v71, v72
	v_max3_f32 v229, v229, v87, v88
	v_max3_f32 v228, v228, v73, v74
	v_max3_f32 v229, v229, v89, v90
	v_max3_f32 v228, v228, v75, v76
	v_max3_f32 v229, v229, v91, v92
	v_max3_f32 v228, v228, v77, v78
	v_max3_f32 v229, v229, v93, v94
	v_max3_f32 v228, v228, v79, v95
	v_max_f32_e32 v228, v228, v229
	s_mov_b32 s5, 2
	v_cmp_ge_f32_e32 vcc, s13, v228
	v_mov_b32_e32 v226, 1.0
	s_cmp_eq_u64 vcc, exec
	s_cbranch_scc0 .Latt_rare

; __device__ __forceinline__ void qkt(f32x16& p0, f32x16& p1, const unsigned char* Ks, const i32x8* qr, int r32, int hi) {
;   p0 = f32x16{}; p1 = f32x16{};
; #pragma unroll
;   for (int m = 0; m < 3; ++m) { const int cb = m * 64 + hi * 32;
;     const u32x4 a0 = *reinterpret_cast<const u32x4*>(Ks + KSWZ(r32, cb)), a1 = *reinterpret_cast<const u32x4*>(Ks + KSWZ(r32, cb) + 16);
;     const u32x4 c0 = *reinterpret_cast<const u32x4*>(Ks + KSWZ(32 + r32, cb)), c1 = *reinterpret_cast<const u32x4*>(Ks + KSWZ(32 + r32, cb) + 16);
;     const i32x8 b0 = {(int)a0.x, (int)a0.y, (int)a0.z, (int)a0.w, (int)a1.x, (int)a1.y, (int)a1.z, (int)a1.w};
;     const i32x8 b1 = {(int)c0.x, (int)c0.y, (int)c0.z, (int)c0.w, (int)c1.x, (int)c1.y, (int)c1.z, (int)c1.w};
;     p0 = __builtin_amdgcn_mfma_scale_f32_32x32x64_f8f6f4(b0, qr[m], p0, 0, 0, 0, 0x7F7F7F7F, 0, 0x7F7F7F7F);
;     p1 = __builtin_amdgcn_mfma_scale_f32_32x32x64_f8f6f4(b1, qr[m], p1, 0, 0, 0, 0x7F7F7F7F, 0, 0x7F7F7F7F); }
.Latt_v_nobar_2:
	s_add_u32 s6, s6, 1
	s_setprio 1
	s_add_u32 s4, s6, 2
	ds_read_b128 v[176:179], v221 offset:20480
	ds_read_b128 v[180:183], v221 offset:20496
	ds_read_b128 v[184:187], v221 offset:23040
	ds_read_b128 v[188:191], v221 offset:23056
	s_waitcnt lgkmcnt(4)
	v_mfma_scale_f32_32x32x64_f8f6f4 v[64:79], v[128:135], v[96:103], v[160:175], v235, v201 op_sel_hi:[0,0,0]
	ds_read_b128 v[128:131], v220 offset:40064
	ds_read_b128 v[132:135], v220 offset:40080
	v_mfma_scale_f32_32x32x64_f8f6f4 v[80:95], v[136:143], v[96:103], v[160:175], v235, v201 op_sel_hi:[0,0,0]
	ds_read_b128 v[136:139], v220 offset:46720
	ds_read_b128 v[140:143], v220 offset:46736
	s_cmp_lt_u32 s4, 128
	s_cbranch_scc0 .Latt_ms3_nowr
	s_waitcnt vmcnt(0)
	ds_write2_b32 v224, v202, v204 offset1:1
	ds_write2_b32 v224, v203, v205 offset0:8 offset1:9
	ds_write_b128 v218, v[206:209] offset:13312
	s_cmp_lt_u32 s12, 4
	s_cbranch_scc0 .Latt_ms3_w1
	ds_write_b128 v219, v[210:213] offset:13312

; __device__ __forceinline__ void partialSM(f32x16& p0, f32x16& p1, float& m_reg, float& mn, float& alpha) {
;   constexpr float C = SCALE * 1.4426950408889634f;
;   float pmax = p0[0]; for (int r = 1; r < 16; ++r) pmax = fmaxf(pmax, p0[r]); for (int r = 0; r < 16; ++r) pmax = fmaxf(pmax, p1[r]);
;   { auto rr = __builtin_amdgcn_permlane32_swap(__float_as_uint(pmax), __float_as_uint(pmax), false, false);
;     pmax = fmaxf(__uint_as_float(rr[0]), __uint_as_float(rr[1])); }
;   if (__builtin_expect(__all(pmax - m_reg <= THR / SCALE), 1)) { mn = m_reg; alpha = 1.f; }
.Latt_m_nobar_3:
	s_setprio 0
	v_max3_f32 v228, v64, v65, v66
	v_max3_f32 v229, v80, v81, v82
	v_max3_f32 v228, v228, v67, v68
	v_max3_f32 v229, v229, v83, v84
	v_max3_f32 v228, v228, v69, v70
	v_max3_f32 v229, v229, v85, v86
	v_max3_f32 v228, v228, v71, v72
	v_max3_f32 v229, v229, v87, v88
	v_max3_f32 v228, v228, v73, v74
	v_max3_f32 v229, v229, v89, v90
	v_max3_f32 v228, v228, v75, v76
	v_max3_f32 v229, v229, v91, v92
	v_max3_f32 v228, v228, v77, v78
	v_max3_f32 v229, v229, v93, v94
	v_max3_f32 v228, v228, v79, v95
	v_max_f32_e32 v228, v228, v229
	s_mov_b32 s5, 3
	v_cmp_ge_f32_e32 vcc, s13, v228
	v_mov_b32_e32 v226, 1.0
	s_cmp_eq_u64 vcc, exec
	s_cbranch_scc0 .Latt_rare
